# P7->P8 and P8->P9 syncs made group-local: the 32 workgroups sharing blockIdx&7 own the same row blocks in P7/P8/P9, each group uses its own counter and flag (L2 write-back and invalidate kept)
# speedup vs baseline: 1.0006x; 1.0006x over previous
.LBB0_528:
	s_waitcnt lgkmcnt(0)
	s_waitcnt vmcnt(0) lgkmcnt(0)
	s_barrier
	s_and_saveexec_b64 s[6:7], s[72:73]
	s_cbranch_execz .LBB0_538
	buffer_wbl2 sc1
	s_load_dwordx2 s[8:9], s[70:71], -0x8
	s_and_b32 s11, s2, 7
	s_lshl_b32 s11, s11, 6
	v_mov_b32_e32 v2, s11
	s_lshr_b32 s10, s33, 3
	v_mov_b32_e32 v3, 1
	s_waitcnt vmcnt(0) lgkmcnt(0)
	global_atomic_add v1, v2, v3, s[8:9] offset:2304 sc0
	s_waitcnt vmcnt(0)
	v_readfirstlane_b32 s11, v1
	s_add_i32 s11, s11, 1
	s_cmp_lg_u32 s11, s10
	s_cbranch_scc1 .Lgb5_poll
	global_atomic_add v2, v3, s[8:9] offset:3200
.Lgb5_poll:
	global_load_dword v1, v2, s[8:9] offset:3200 sc1
	s_waitcnt vmcnt(0)
	v_readfirstlane_b32 s11, v1
	s_cmp_ge_u32 s11, 1
	s_cbranch_scc1 .Lgb5_acq
	s_sleep 1
	s_branch .Lgb5_poll

.LBB0_554:
	s_waitcnt vmcnt(0) lgkmcnt(0)
	s_barrier
	s_and_saveexec_b64 s[6:7], s[72:73]
	s_cbranch_execz .LBB0_564
	buffer_wbl2 sc1
	s_load_dwordx2 s[8:9], s[70:71], -0x8
	s_and_b32 s11, s2, 7
	s_lshl_b32 s11, s11, 6
	v_mov_b32_e32 v2, s11
	s_lshr_b32 s10, s33, 3
	s_lshl_b32 s10, s10, 1
	v_mov_b32_e32 v3, 1
	s_waitcnt vmcnt(0) lgkmcnt(0)
	global_atomic_add v1, v2, v3, s[8:9] offset:2304 sc0
	s_waitcnt vmcnt(0)
	v_readfirstlane_b32 s11, v1
	s_add_i32 s11, s11, 1
	s_cmp_lg_u32 s11, s10
	s_cbranch_scc1 .Lgb6_poll
	global_atomic_add v2, v3, s[8:9] offset:3200
.Lgb6_poll:
	global_load_dword v1, v2, s[8:9] offset:3200 sc1
	s_waitcnt vmcnt(0)
	v_readfirstlane_b32 s11, v1
	s_cmp_ge_u32 s11, 2
	s_cbranch_scc1 .Lgb6_acq
	s_sleep 1
	s_branch .Lgb6_poll
